# code prefetch touches issued behind the first barrier poll and into an LDS scratch area (LDS-DMA), so the last arriver does not wait for them
# baseline (speedup 1.0000x reference)
.Lxb0_wait:
	global_load_dword v7, v6, s[92:93] sc1
	s_getpc_b64 s[10:11]
.Lxb0_ic:
	s_add_u32 s10, s10, .Lxb0_done-.Lxb0_ic
	s_addc_u32 s11, s11, 0
	s_mov_b64 exec, -1
	v_mbcnt_lo_u32_b32 v8, -1, 0
	v_mbcnt_hi_u32_b32 v8, -1, v8
	v_lshlrev_b32_e32 v8, 6, v8
	s_mov_b32 m0, 0x23400
	s_nop 0
	global_load_lds_dword v8, s[10:11]
	s_add_u32 s10, s10, 0x1000
	s_addc_u32 s11, s11, 0
	global_load_lds_dword v8, s[10:11]
	s_mov_b64 exec, 1
	s_waitcnt vmcnt(2)
	v_readfirstlane_b32 s12, v7
	s_cmp_ge_u32 s12, s6
	s_cbranch_scc1 .Lxb0_done
	s_mov_b32 s11, 0

.Lxb0_done:
	s_waitcnt vmcnt(2)
	v_mov_b32_e32 v8, 0x5000
	global_load_dword v9, v8, s[92:93] sc1
	global_load_dword v10, v8, s[92:93] offset:256 sc1
	global_load_dword v11, v8, s[92:93] offset:512 sc1
	global_load_dword v12, v8, s[92:93] offset:768 sc1
	global_load_dword v13, v8, s[92:93] offset:1024 sc1
	global_load_dword v14, v8, s[92:93] offset:1280 sc1
	global_load_dword v15, v8, s[92:93] offset:1536 sc1
	global_load_dword v16, v8, s[92:93] offset:1792 sc1
	s_waitcnt vmcnt(0)
	v_mov_b32_e32 v2, 0
	v_add_u32_e32 v3, -1, v9
	v_and_b32_e32 v3, v3, v9
	v_or_b32_e32 v2, v2, v3
	v_add_u32_e32 v3, -1, v10
	v_and_b32_e32 v3, v3, v10
	v_or_b32_e32 v2, v2, v3
	v_add_u32_e32 v3, -1, v11
	v_and_b32_e32 v3, v3, v11
	v_or_b32_e32 v2, v2, v3
	v_add_u32_e32 v3, -1, v12
	v_and_b32_e32 v3, v3, v12
	v_or_b32_e32 v2, v2, v3
	v_add_u32_e32 v3, -1, v13
	v_and_b32_e32 v3, v3, v13
	v_or_b32_e32 v2, v2, v3
	v_add_u32_e32 v3, -1, v14
	v_and_b32_e32 v3, v3, v14
	v_or_b32_e32 v2, v2, v3
	v_add_u32_e32 v3, -1, v15
	v_and_b32_e32 v3, v3, v15
	v_or_b32_e32 v2, v2, v3
	v_add_u32_e32 v3, -1, v16
	v_and_b32_e32 v3, v3, v16
	v_or_b32_e32 v2, v2, v3
	s_nop 0
	v_readfirstlane_b32 s12, v2
	v_readlane_b32 s11, v244, 41
	s_cmp_eq_u32 s12, 0
	s_cselect_b32 s12, 1, 0
	s_cmp_eq_u32 s11, 0x100
	s_cselect_b32 s12, s12, 0
	s_nop 0
	v_writelane_b32 v244, s12, 43
	v_mov_b32_e32 v0, 0x23fc8
	v_mov_b32_e32 v2, s12
	ds_write_b32 v0, v2
	s_waitcnt lgkmcnt(0)

.Lxb1_ic:
	s_add_u32 s10, s10, .Lxb1_done-.Lxb1_ic
	s_addc_u32 s11, s11, 0
	s_mov_b64 exec, -1
	v_mbcnt_lo_u32_b32 v8, -1, 0
	v_mbcnt_hi_u32_b32 v8, -1, v8
	v_lshlrev_b32_e32 v8, 6, v8
	s_mov_b32 m0, 0x23400
	s_nop 0
	global_load_lds_dword v8, s[10:11]
	s_add_u32 s10, s10, 0x1000
	s_addc_u32 s11, s11, 0
	global_load_lds_dword v8, s[10:11]
	s_add_u32 s10, s10, 0x1000
	s_addc_u32 s11, s11, 0
	global_load_lds_dword v8, s[10:11]
	s_add_u32 s10, s10, 0x1000
	s_addc_u32 s11, s11, 0
	global_load_lds_dword v8, s[10:11]
	s_add_u32 s10, s10, 0x1000
	s_addc_u32 s11, s11, 0
	global_load_lds_dword v8, s[10:11]
	s_mov_b64 exec, 1
	s_waitcnt vmcnt(5)
	v_readfirstlane_b32 s12, v7
	s_cmp_ge_u32 s12, s6
	s_cbranch_scc1 .Lxb1_done
	s_mov_b32 s11, 0
.Lxb1_poll:
	global_load_dword v7, v6, s[92:93] sc1
	s_waitcnt vmcnt(0)
	v_readfirstlane_b32 s12, v7
	s_cmp_ge_u32 s12, s6
	s_cbranch_scc1 .Lxb1_done
	s_add_i32 s11, s11, 1
	s_cmp_lt_u32 s11, 0x40000
	s_cbranch_scc0 .Lxb1_done
	s_sleep 1
	s_branch .Lxb1_poll
.Lxb1_done:
	s_waitcnt vmcnt(5)
.LBB0_257:
	s_or_b64 exec, exec, s[4:5]

.Lxb2_ic:
	s_add_u32 s10, s10, .Lxb2_done-.Lxb2_ic
	s_addc_u32 s11, s11, 0
	s_mov_b64 exec, -1
	v_mbcnt_lo_u32_b32 v8, -1, 0
	v_mbcnt_hi_u32_b32 v8, -1, v8
	v_lshlrev_b32_e32 v8, 6, v8
	s_mov_b32 m0, 0x23400
	s_nop 0
	global_load_lds_dword v8, s[10:11]
	s_mov_b64 exec, 1
	s_waitcnt vmcnt(1)
	v_readfirstlane_b32 s12, v7
	s_cmp_ge_u32 s12, s6
	s_cbranch_scc1 .Lxb2_done
	s_mov_b32 s11, 0
.Lxb2_poll:
	global_load_dword v7, v6, s[92:93] sc1
	s_waitcnt vmcnt(0)
	v_readfirstlane_b32 s12, v7
	s_cmp_ge_u32 s12, s6
	s_cbranch_scc1 .Lxb2_done
	s_add_i32 s11, s11, 1
	s_cmp_lt_u32 s11, 0x40000
	s_cbranch_scc0 .Lxb2_done
	s_sleep 1
	s_branch .Lxb2_poll
.Lxb2_done:
	s_waitcnt vmcnt(1)
.LBB0_549:
	s_or_b64 exec, exec, s[0:1]

.Lxb3_ic:
	s_add_u32 s10, s10, .Lxb3_done-.Lxb3_ic
	s_addc_u32 s11, s11, 0
	s_mov_b64 exec, -1
	v_mbcnt_lo_u32_b32 v8, -1, 0
	v_mbcnt_hi_u32_b32 v8, -1, v8
	v_lshlrev_b32_e32 v8, 6, v8
	s_mov_b32 m0, 0x23400
	s_nop 0
	global_load_lds_dword v8, s[10:11]
	s_add_u32 s10, s10, 0x1000
	s_addc_u32 s11, s11, 0
	global_load_lds_dword v8, s[10:11]
	s_add_u32 s10, s10, 0x1000
	s_addc_u32 s11, s11, 0
	global_load_lds_dword v8, s[10:11]
	s_add_u32 s10, s10, 0x1000
	s_addc_u32 s11, s11, 0
	global_load_lds_dword v8, s[10:11]
	s_mov_b64 exec, 1
	s_waitcnt vmcnt(4)
	v_readfirstlane_b32 s12, v7
	s_cmp_ge_u32 s12, s6
	s_cbranch_scc1 .Lxb3_done
	s_mov_b32 s11, 0
.Lxb3_poll:
	global_load_dword v7, v6, s[92:93] sc1
	s_waitcnt vmcnt(0)
	v_readfirstlane_b32 s12, v7
	s_cmp_ge_u32 s12, s6
	s_cbranch_scc1 .Lxb3_done
	s_add_i32 s11, s11, 1
	s_cmp_lt_u32 s11, 0x40000
	s_cbranch_scc0 .Lxb3_done
	s_sleep 1
	s_branch .Lxb3_poll
.Lxb3_done:
	s_waitcnt vmcnt(4)
.LBB0_628:
	s_or_b64 exec, exec, s[0:1]

.Lxb4_poll:
	global_load_dword v7, v6, s[92:93] sc1
	s_waitcnt vmcnt(0)
	v_readfirstlane_b32 s12, v7
	s_cmp_ge_u32 s12, s6
	s_cbranch_scc1 .Lxb4_done
	s_add_i32 s11, s11, 1
	s_cmp_lt_u32 s11, 0x40000
	s_cbranch_scc0 .Lxb4_done
	s_sleep 1
	s_branch .Lxb4_poll
.Lxb4_done:
	s_waitcnt vmcnt(4)
.LBB0_738:
	s_or_b64 exec, exec, s[4:5]

.Lxb5_done:
	s_waitcnt vmcnt(2)

.Lxb6_ic:
	s_add_u32 s10, s10, .Lxb6_done-.Lxb6_ic
	s_addc_u32 s11, s11, 0
	s_mov_b64 exec, -1
	v_mbcnt_lo_u32_b32 v8, -1, 0
	v_mbcnt_hi_u32_b32 v8, -1, v8
	v_lshlrev_b32_e32 v8, 6, v8
	s_mov_b32 m0, 0x23400
	s_nop 0
	global_load_lds_dword v8, s[10:11]
	s_add_u32 s10, s10, 0x1000
	s_addc_u32 s11, s11, 0
	global_load_lds_dword v8, s[10:11]
	s_add_u32 s10, s10, 0x1000
	s_addc_u32 s11, s11, 0
	global_load_lds_dword v8, s[10:11]
	s_mov_b64 exec, 1
	s_waitcnt vmcnt(3)
	v_readfirstlane_b32 s12, v7
	s_cmp_ge_u32 s12, s6
	s_cbranch_scc1 .Lxb6_done
	s_mov_b32 s11, 0

.Lxb6_done:
	s_waitcnt vmcnt(3)
